# P7 select + P9 own: query-row loads issued before the barrier/image waits
# baseline (speedup 1.0000x reference)
; #define LAS __attribute__((address_space(3)))
; __device__ __forceinline__ unsigned pkh(float lo, float hi) { f32x2 v = {lo, hi}; h16x2 h = __builtin_convertvector(v, h16x2); return __builtin_bit_cast(unsigned, h); }
; __device__ __forceinline__ void moba_select(const Frame& F, const Args& a) {
;     ...
;     for (int unit = F.vcu; unit < BATCH * NBLK * MOBA_H; unit += F.G) {
;         const int h = unit % MOBA_H, qb = (unit / MOBA_H) % NBLK, b = unit / (MOBA_H * NBLK);
;         const size_t ub = (size_t)(b * MOBA_H + h) * NBLK + qb;
;         __syncthreads();
;         if (tid < 64) { cnt[tid] = 0; cur[tid] = 0; }
;         { const int j = tid >> 3, c = tid & 7; const float* src = kmean + ((size_t)(b * MOBA_H + h) * NBLK + j) * HD + 8 * c;
;           const f32x4 x0 = *(const f32x4*)src, x1 = *(const f32x4*)(src + 4);
;           const float v[8] = {x0[0], x0[1], x0[2], x0[3], x1[0], x1[1], x1[2], x1[3]}; float hi[8], lo[8];
; #pragma unroll
;           for (int e = 0; e < 8; ++e) { hi[e] = (float)(_Float16)v[e]; lo[e] = v[e] - hi[e]; }
;           u32x4 wh, wl; wh.x = pkh(hi[0], hi[1]); wh.y = pkh(hi[2], hi[3]); wh.z = pkh(hi[4], hi[5]); wh.w = pkh(hi[6], hi[7]);
;           wl.x = pkh(lo[0], lo[1]); wl.y = pkh(lo[2], lo[3]); wl.z = pkh(lo[4], lo[5]); wl.w = pkh(lo[6], lo[7]);
;           *(LAS u32x4*)(KMhi + j * 128 + ((c ^ (j & 7)) << 4)) = wh; *(LAS u32x4*)(KMlo + j * 128 + ((c ^ (j & 7)) << 4)) = wl; }
;         __syncthreads();
;         const int nsel = qb < 3 ? qb : 3, njt = qb > 0 ? ((qb - 1) >> 4) + 1 : 0;
;         int isel[2] = {0, 0};
; #pragma unroll
;         for (int rep = 0; rep < 2; ++rep) {
;             const int qi = 16 * (w + 8 * rep) + fr;
;             const f16_t* qp = P + (size_t)(b * SEQ + qb * MOBA_BLK + qi) * NB + h * HD + 8 * G;
;             const h16x8 q0 = *(const h16x8*)qp, q1 = *(const h16x8*)(qp + 32);
;             unsigned t0 = 0u, t1 = 0u, t2 = 0u;
;             const int kof0 = fr * 128 + (((0 + G) ^ (fr & 7)) << 4), kof1 = fr * 128 + (((4 + G) ^ (fr & 7)) << 4);
;             for (int jt = 0; jt < njt; ++jt) {
.LBB0_867:
	s_barrier
	s_and_saveexec_b64 s[18:19], s[94:95]
	ds_write2_b32 v53, v21, v21 offset1:136
	s_or_b64 exec, exec, s[18:19]
	s_mul_hi_i32 s18, s43, 0x2aaaaaab
	s_ashr_i32 s19, s18, 1
	s_lshr_b32 s20, s18, 31
	s_add_i32 s19, s19, s20
	s_ashr_i32 s18, s18, 7
	s_mul_i32 s21, s19, 12
	s_add_i32 s20, s18, s20
	s_sub_i32 s21, s43, s21
	s_mul_i32 s18, s20, 12
	s_add_i32 s28, s18, s21
	s_ashr_i32 s29, s28, 31
	s_lshl_b64 s[30:31], s[28:29], 6
	v_mov_b32_e32 v7, s31
	v_or_b32_e32 v6, s30, v18
	v_lshlrev_b64 v[6:7], 8, v[6:7]
	v_lshl_add_u64 v[10:11], v[22:23], 0, v[6:7]
	global_load_dwordx4 v[6:9], v[10:11], off
	s_nop 0
	global_load_dwordx4 v[10:13], v[10:11], off offset:16
	s_ashr_i32 s18, s19, 31
	s_lshr_b32 s18, s18, 26
	s_add_i32 s18, s19, s18
	s_andn2_b32 s18, s18, 63
	s_sub_i32 s29, s19, s18
	s_ashr_i32 s36, s29, 31
	s_cmp_gt_i32 s29, 0
	s_cselect_b64 s[18:19], -1, 0
	s_add_i32 s34, s29, -1
	s_lshl_b32 s35, s20, 14
	s_lshl_b32 s44, s29, 8
	s_lshl_b32 s20, s21, 6
	s_ashr_i32 s37, s34, 4
	s_add_i32 s44, s44, s35
	s_ashr_i32 s21, s20, 31
	s_cmp_gt_i32 s37, -1
	v_lshl_add_u64 v[30:31], s[20:21], 1, v[24:25]
	s_cselect_b64 s[20:21], -1, 0
	s_and_b64 s[18:19], s[18:19], s[20:21]
	v_cndmask_b32_e64 v14, 0, 1, s[18:19]
	v_cmp_ne_u32_e64 s[20:21], 1, v14
	v_mov_b32_e32 v20, 0
	v_mov_b32_e32 v56, 0
	v_add_u32_e32 v55, s44, v33
	v_mad_i64_i32 v[14:15], vcc, v55, s42, v[30:31]
	global_load_dwordx4 v[240:243], v[14:15], off
	global_load_dwordx4 v[244:247], v[14:15], off offset:64
	v_add_u32_e32 v16, 0x80, v55
	v_mad_i64_i32 v[14:15], vcc, v16, s42, v[30:31]
	global_load_dwordx4 v[248:251], v[14:15], off
	global_load_dwordx4 v[252:255], v[14:15], off offset:64
	s_andn2_b64 vcc, exec, s[18:19]
	s_waitcnt vmcnt(5)
	v_cvt_f16_f32_e32 v14, v6
	v_cvt_f16_f32_e32 v15, v7
	v_cvt_f16_f32_e32 v16, v8
	v_cvt_f16_f32_e32 v17, v9
	s_waitcnt vmcnt(4)
	v_cvt_f16_f32_e32 v57, v10
	v_cvt_f16_f32_e32 v58, v11
	v_cvt_f16_f32_e32 v59, v12
	v_cvt_f16_f32_e32 v60, v13
	v_cvt_f32_f16_e32 v14, v14
	v_cvt_f32_f16_e32 v15, v15
	v_cvt_f32_f16_e32 v16, v16
	v_cvt_f32_f16_e32 v17, v17
	v_cvt_f32_f16_e32 v57, v57
	v_cvt_f32_f16_e32 v58, v58
	v_cvt_f32_f16_e32 v59, v59
	v_cvt_f32_f16_e32 v60, v60
	v_sub_f32_e32 v61, v6, v14
	v_sub_f32_e32 v62, v7, v15
	v_sub_f32_e32 v63, v8, v16
	v_sub_f32_e32 v64, v9, v17
	v_sub_f32_e32 v65, v10, v57
	v_sub_f32_e32 v66, v11, v58
	v_sub_f32_e32 v67, v12, v59
	v_sub_f32_e32 v13, v13, v60
	v_cvt_pk_f16_f32 v6, v14, v15
	v_cvt_pk_f16_f32 v7, v16, v17
	v_cvt_pk_f16_f32 v8, v57, v58
	v_cvt_pk_f16_f32 v9, v59, v60
	v_mov_b32_e32 v57, 0
	v_cvt_pk_f16_f32 v10, v61, v62
	v_cvt_pk_f16_f32 v11, v63, v64
	v_cvt_pk_f16_f32 v12, v65, v66
	v_cvt_pk_f16_f32 v13, v67, v13
	ds_write_b128 v51, v[6:9]
	ds_write_b128 v51, v[10:13] offset:8192
	s_waitcnt lgkmcnt(0)
	s_barrier
	s_cbranch_vccnz .LBB0_880
	s_add_i32 s34, s37, 1
	v_mov_b32_e32 v20, 0
	v_mov_b32_e32 v58, v49
	v_mov_b32_e32 v59, v48
	v_mov_b32_e32 v60, v40
	v_mov_b32_e32 v61, v47
	v_mov_b32_e32 v56, 0
	v_mov_b32_e32 v57, 0
	s_branch .LBB0_872

; #define LAS __attribute__((address_space(3)))
; #define SEL_INSERT(k) do { const unsigned a_ = min(t0, (k)); t0 = max(t0, (k)); const unsigned b_ = min(t1, a_); t1 = max(t1, a_); t2 = max(t2, b_); } while (0)
; __device__ __forceinline__ void moba_select(const Frame& F, const Args& a) {
;     ...
;             for (int jt = 0; jt < njt; ++jt) {
;                 f32x4 acc = {0.f, 0.f, 0.f, 0.f};
;                 acc = __builtin_amdgcn_mfma_f32_16x16x32_f16(*(LAS const h16x8*)(KMhi + jt * 2048 + kof0), q0, acc, 0, 0, 0);
;                 acc = __builtin_amdgcn_mfma_f32_16x16x32_f16(*(LAS const h16x8*)(KMhi + jt * 2048 + kof1), q1, acc, 0, 0, 0);
;                 acc = __builtin_amdgcn_mfma_f32_16x16x32_f16(*(LAS const h16x8*)(KMlo + jt * 2048 + kof0), q0, acc, 0, 0, 0);
;                 acc = __builtin_amdgcn_mfma_f32_16x16x32_f16(*(LAS const h16x8*)(KMlo + jt * 2048 + kof1), q1, acc, 0, 0, 0);
; #pragma unroll
;                 for (int e = 0; e < 4; ++e) { const int j = 16 * jt + 4 * G + e; const unsigned k = (j < qb) ? sel_key(acc[e], j) : 0u; SEL_INSERT(k); }
;             }
; #pragma unroll
;             for (int x = 16; x <= 32; x <<= 1) {
;                 const unsigned p0 = (unsigned)__shfl_xor((int)t0, x), p1 = (unsigned)__shfl_xor((int)t1, x), p2 = (unsigned)__shfl_xor((int)t2, x);
;                 SEL_INSERT(p0); SEL_INSERT(p1); SEL_INSERT(p2);
;             }
;             const unsigned tk = (G == 0) ? t0 : (G == 1) ? t1 : t2;
;             isel[rep] = 63 - (int)(tk & 63u);
;             if (G < nsel) __hip_atomic_fetch_add(cnt + isel[rep], 1, __ATOMIC_RELAXED, __HIP_MEMORY_SCOPE_WORKGROUP);
.LBB0_872:
	ds_read_b128 v[14:17], v58
	ds_read_b128 v[62:65], v58 offset:8192
	ds_read_b128 v[66:69], v59
	ds_read_b128 v[70:73], v59 offset:8192
	v_cmp_gt_i32_e32 vcc, s29, v60
	s_waitcnt vmcnt(3) lgkmcnt(3)
	v_mfma_f32_16x16x32_f16 v[14:17], v[14:17], v[240:243], 0
	s_waitcnt vmcnt(2) lgkmcnt(1)
	v_mfma_f32_16x16x32_f16 v[14:17], v[66:69], v[244:247], v[14:17]
	v_mfma_f32_16x16x32_f16 v[14:17], v[62:65], v[240:243], v[14:17]
	v_mov_b32_e32 v62, 0
	s_waitcnt lgkmcnt(0)
	v_mfma_f32_16x16x32_f16 v[14:17], v[70:73], v[244:247], v[14:17]
	s_and_saveexec_b64 s[18:19], vcc
	s_nop 6
	v_not_b32_e32 v62, v14
	v_or_b32_e32 v63, 0x80000000, v14
	v_cmp_gt_i32_e32 vcc, 0, v14
	s_nop 1
	v_cndmask_b32_e32 v14, v63, v62, vcc
	v_and_or_b32 v62, v14, s41, v61
	s_or_b64 exec, exec, s[18:19]
	v_add_u32_e32 v14, 1, v60
	v_cmp_gt_i32_e32 vcc, s29, v14
	v_mov_b32_e32 v14, 0
	v_mov_b32_e32 v63, 0
	s_and_saveexec_b64 s[18:19], vcc
	v_not_b32_e32 v63, v15
	v_or_b32_e32 v64, 0x80000000, v15
	v_cmp_gt_i32_e32 vcc, 0, v15
	s_nop 1
	v_cndmask_b32_e32 v15, v64, v63, vcc
	v_add_u32_e32 v63, -1, v61
	v_and_or_b32 v63, v15, s41, v63
	s_or_b64 exec, exec, s[18:19]
	v_add_u32_e32 v15, 2, v60
	v_cmp_gt_i32_e32 vcc, s29, v15
	s_and_saveexec_b64 s[18:19], vcc
	v_not_b32_e32 v14, v16
	v_or_b32_e32 v15, 0x80000000, v16
	v_cmp_gt_i32_e32 vcc, 0, v16
	s_nop 1
	v_cndmask_b32_e32 v14, v15, v14, vcc
	v_add_u32_e32 v15, -2, v61
	v_and_or_b32 v14, v14, s41, v15
	s_or_b64 exec, exec, s[18:19]
	v_add_u32_e32 v15, 3, v60
	v_cmp_gt_i32_e32 vcc, s29, v15
	v_mov_b32_e32 v15, 0
	s_and_saveexec_b64 s[18:19], vcc
	s_cbranch_execz .LBB0_871
	v_not_b32_e32 v15, v17
	v_or_b32_e32 v16, 0x80000000, v17
	v_cmp_gt_i32_e32 vcc, 0, v17
	s_nop 1
	v_cndmask_b32_e32 v15, v16, v15, vcc
	v_add_u32_e32 v16, -3, v61
	v_and_or_b32 v15, v15, s41, v16
	s_branch .LBB0_871
.LBB0_880:
	ds_bpermute_b32 v6, v27, v20
	ds_bpermute_b32 v7, v27, v56
	ds_bpermute_b32 v8, v27, v57
	s_min_i32 s18, s29, 3
	v_cmp_gt_i32_e64 s[18:19], s18, v19
	s_waitcnt lgkmcnt(2)
	v_min_u32_e32 v9, v20, v6
	v_max_u32_e32 v6, v20, v6
	v_min_u32_e32 v10, v56, v9
	v_max_u32_e32 v9, v56, v9
	s_waitcnt lgkmcnt(1)
	v_min_u32_e32 v11, v6, v7
	v_max_u32_e32 v6, v6, v7
	v_min_u32_e32 v7, v9, v11
	v_max_u32_e32 v9, v9, v11
	s_waitcnt lgkmcnt(0)
	v_min_u32_e32 v11, v6, v8
	v_max_u32_e32 v6, v6, v8
	v_max_u32_e32 v10, v57, v10
	v_min_u32_e32 v8, v9, v11
	ds_bpermute_b32 v12, v35, v6
	v_max_u32_e32 v9, v9, v11
	v_max3_u32 v7, v10, v7, v8
	ds_bpermute_b32 v8, v35, v9
	ds_bpermute_b32 v10, v35, v7
	s_waitcnt lgkmcnt(2)
	v_min_u32_e32 v11, v6, v12
	v_max_u32_e32 v6, v6, v12
	v_min_u32_e32 v12, v9, v11
	v_max_u32_e32 v9, v9, v11
	s_waitcnt lgkmcnt(1)
	v_min_u32_e32 v11, v6, v8
	v_max_u32_e32 v6, v6, v8
	v_min_u32_e32 v8, v9, v11
	v_max_u32_e32 v9, v9, v11
	s_waitcnt lgkmcnt(0)
	v_min_u32_e32 v11, v6, v10
	v_max_u32_e32 v7, v7, v12
	v_max_u32_e32 v6, v6, v10
	v_min_u32_e32 v10, v9, v11
	v_max_u32_e32 v9, v9, v11
	v_max3_u32 v7, v7, v8, v10
	v_cndmask_b32_e64 v7, v7, v9, s[2:3]
	v_cndmask_b32_e64 v6, v7, v6, s[0:1]
	v_bitop3_b32 v6, v6, 63, v6 bitop3:0xc
	v_lshl_add_u32 v20, v6, 2, 0
	s_and_saveexec_b64 s[34:35], s[18:19]
	ds_add_u32 v20, v52 offset:16384
	s_or_b64 exec, exec, s[34:35]
	v_mov_b32_e32 v56, 0
	s_and_b64 vcc, exec, s[20:21]
	v_mov_b32_e32 v58, 0
	v_mov_b32_e32 v57, 0
	s_cbranch_vccnz .LBB0_893
	s_add_i32 s34, s37, 1
	v_mov_b32_e32 v56, 0
	v_mov_b32_e32 v30, v49
	v_mov_b32_e32 v31, v48
	v_mov_b32_e32 v55, v40
	v_mov_b32_e32 v59, v47
	v_mov_b32_e32 v58, 0
	v_mov_b32_e32 v57, 0
	s_branch .LBB0_885

; #define LAS __attribute__((address_space(3)))
; #define SEL_INSERT(k) do { const unsigned a_ = min(t0, (k)); t0 = max(t0, (k)); const unsigned b_ = min(t1, a_); t1 = max(t1, a_); t2 = max(t2, b_); } while (0)
; __device__ __forceinline__ void moba_select(const Frame& F, const Args& a) {
;     ...
;             for (int jt = 0; jt < njt; ++jt) {
;                 f32x4 acc = {0.f, 0.f, 0.f, 0.f};
;                 acc = __builtin_amdgcn_mfma_f32_16x16x32_f16(*(LAS const h16x8*)(KMhi + jt * 2048 + kof0), q0, acc, 0, 0, 0);
;                 acc = __builtin_amdgcn_mfma_f32_16x16x32_f16(*(LAS const h16x8*)(KMhi + jt * 2048 + kof1), q1, acc, 0, 0, 0);
;                 acc = __builtin_amdgcn_mfma_f32_16x16x32_f16(*(LAS const h16x8*)(KMlo + jt * 2048 + kof0), q0, acc, 0, 0, 0);
;                 acc = __builtin_amdgcn_mfma_f32_16x16x32_f16(*(LAS const h16x8*)(KMlo + jt * 2048 + kof1), q1, acc, 0, 0, 0);
; #pragma unroll
;                 for (int e = 0; e < 4; ++e) { const int j = 16 * jt + 4 * G + e; const unsigned k = (j < qb) ? sel_key(acc[e], j) : 0u; SEL_INSERT(k); }
;             }
.LBB0_885:
	ds_read_b128 v[14:17], v30
	ds_read_b128 v[60:63], v30 offset:8192
	ds_read_b128 v[64:67], v31
	ds_read_b128 v[68:71], v31 offset:8192
	v_cmp_gt_i32_e32 vcc, s29, v55
	s_waitcnt vmcnt(1) lgkmcnt(3)
	v_mfma_f32_16x16x32_f16 v[14:17], v[14:17], v[248:251], 0
	s_waitcnt vmcnt(0) lgkmcnt(1)
	v_mfma_f32_16x16x32_f16 v[14:17], v[64:67], v[252:255], v[14:17]
	v_mfma_f32_16x16x32_f16 v[14:17], v[60:63], v[248:251], v[14:17]
	v_mov_b32_e32 v60, 0
	s_waitcnt lgkmcnt(0)
	v_mfma_f32_16x16x32_f16 v[14:17], v[68:71], v[252:255], v[14:17]
	s_and_saveexec_b64 s[20:21], vcc
	s_nop 6
	v_not_b32_e32 v60, v14
	v_or_b32_e32 v61, 0x80000000, v14
	v_cmp_gt_i32_e32 vcc, 0, v14
	s_nop 1
	v_cndmask_b32_e32 v14, v61, v60, vcc
	v_and_or_b32 v60, v14, s41, v59
	s_or_b64 exec, exec, s[20:21]
	v_add_u32_e32 v14, 1, v55
	v_cmp_gt_i32_e32 vcc, s29, v14
	v_mov_b32_e32 v14, 0
	v_mov_b32_e32 v61, 0
	s_and_saveexec_b64 s[20:21], vcc
	v_not_b32_e32 v61, v15
	v_or_b32_e32 v62, 0x80000000, v15
	v_cmp_gt_i32_e32 vcc, 0, v15
	s_nop 1
	v_cndmask_b32_e32 v15, v62, v61, vcc
	v_add_u32_e32 v61, -1, v59
	v_and_or_b32 v61, v15, s41, v61
	s_or_b64 exec, exec, s[20:21]
	v_add_u32_e32 v15, 2, v55
	v_cmp_gt_i32_e32 vcc, s29, v15
	s_and_saveexec_b64 s[20:21], vcc
	v_not_b32_e32 v14, v16
	v_or_b32_e32 v15, 0x80000000, v16
	v_cmp_gt_i32_e32 vcc, 0, v16
	s_nop 1
	v_cndmask_b32_e32 v14, v15, v14, vcc
	v_add_u32_e32 v15, -2, v59
	v_and_or_b32 v14, v14, s41, v15
	s_or_b64 exec, exec, s[20:21]
	v_add_u32_e32 v15, 3, v55
	v_cmp_gt_i32_e32 vcc, s29, v15
	v_mov_b32_e32 v15, 0
	s_and_saveexec_b64 s[20:21], vcc
	s_cbranch_execz .LBB0_884
	v_not_b32_e32 v15, v17
	v_or_b32_e32 v16, 0x80000000, v17
	v_cmp_gt_i32_e32 vcc, 0, v17
	s_nop 1
	v_cndmask_b32_e32 v15, v16, v15, vcc
	v_add_u32_e32 v16, -3, v59
	v_and_or_b32 v15, v15, s41, v16
	s_branch .LBB0_884

; #define VM_WAIT() asm volatile("s_waitcnt vmcnt(0)" ::: "memory")
; template <bool PR_ENG, bool PR_PART, bool PR_ST>
; __device__ __forceinline__ void moba_own(const Frame& F, const Args& a) {
;     ...
;     for (int up = F.vcu; up < BATCH * MOBA_H * NBLK / 2; up += F.G) {
;         const int bh = up / (NBLK / 2), b = bh / MOBA_H, h = bh % MOBA_H, qb0 = 2 * (up % (NBLK / 2));
;         __syncthreads();
; #pragma unroll
;         for (int k = 0; k < 2; ++k) { const f16_t* kb = P + (size_t)(b * SEQ + (qb0 + k) * MOBA_BLK) * NB + MIXW + h * HD;
;             dma_kv_imgs(F.lds + k * 65536, F.lds + k * 65536 + 32768, kb, kb + MIXW, w, lane); }
;         const int dt0 = w, dt1 = 7 - w;
;         const int tq[2][2] = {{qb0 * MOBA_BLK + 32 * dt0 + fr, qb0 * MOBA_BLK + 32 * dt0 + 16 + fr}, {(qb0 + 1) * MOBA_BLK + 32 * dt1 + fr, (qb0 + 1) * MOBA_BLK + 32 * dt1 + 16 + fr}};
;         VM_WAIT();
;         __syncthreads();
; #pragma unroll
;         for (int k = 0; k < 2; ++k) {
;             const int qb = qb0 + k, nsel = qb < 3 ? qb : 3, dti = k ? dt1 : dt0;
;             const int ta = tq[k][0], tb = tq[k][1];
;             h16x8 q0[2][2], q1[2][2]; float mb[2][2];
; #pragma unroll
;             for (int t = 0; t < 2; ++t) moba_load_q(P + (size_t)(b * SEQ + tq[k][t]) * NB + h * HD, G, maxgk, q0[k][t], q1[k][t], mb[k][t]);
.LBB0_1224:
	s_ashr_i32 s0, s51, 31
	s_lshr_b32 s0, s0, 27
	s_add_i32 s0, s51, s0
	s_mul_hi_i32 s1, s51, 0x2aaaaaab
	s_ashr_i32 s20, s0, 5
	s_lshr_b32 s2, s1, 31
	s_lshr_b32 s1, s1, 6
	s_add_i32 s1, s1, s2
	s_mul_hi_i32 s2, s20, 0x2aaaaaab
	s_lshr_b32 s3, s2, 31
	s_lshr_b32 s2, s2, 1
	s_add_i32 s2, s2, s3
	s_andn2_b32 s0, s0, 31
	s_mul_i32 s2, s2, 12
	s_sub_i32 s52, s51, s0
	s_sub_i32 s2, s20, s2
	s_lshl_b32 s53, s1, 14
	s_lshl_b32 s54, s52, 9
	s_lshl_b32 s22, s2, 6
	s_add_i32 s21, s54, s53
	s_ashr_i32 s23, s22, 31
	s_mul_i32 s1, s21, 0x1400
	s_mul_hi_i32 s0, s21, 0x1400
	s_add_u32 s2, s58, s1
	s_addc_u32 s3, s59, s0
	s_lshl_b64 s[0:1], s[22:23], 1
	s_add_u32 s2, s2, s0
	s_addc_u32 s3, s3, s1
	v_mov_b32_e32 v169, v163
	v_lshl_add_u64 v[2:3], s[2:3], 0, v[168:169]
	v_mov_b32_e32 v171, v163
	v_lshl_add_u64 v[2:3], v[2:3], 0, s[14:15]
	v_lshl_add_u64 v[4:5], s[2:3], 0, v[170:171]
	s_barrier
	v_lshl_add_u64 v[4:5], v[4:5], 0, s[16:17]
	v_lshl_add_u64 v[6:7], v[2:3], 0, v[172:173]
	s_mov_b32 s2, m0
	s_mov_b32 m0, s35
	s_nop 0
	global_load_lds_dwordx4 v[6:7], off
	s_mov_b32 m0, s2
	v_lshl_add_u64 v[6:7], v[4:5], 0, v[172:173]
	s_mov_b32 s2, m0
	s_mov_b32 m0, s36
	s_nop 0
	global_load_lds_dwordx4 v[6:7], off
	s_mov_b32 m0, s2
	v_lshl_add_u64 v[6:7], v[2:3], 0, v[174:175]
	s_mov_b32 s2, m0
	s_mov_b32 m0, s37
	s_nop 0
	global_load_lds_dwordx4 v[6:7], off
	s_mov_b32 m0, s2
	v_lshl_add_u64 v[6:7], v[4:5], 0, v[174:175]
	s_mov_b32 s2, m0
	s_mov_b32 m0, s38
	s_nop 0
	global_load_lds_dwordx4 v[6:7], off
	s_mov_b32 m0, s2
	v_lshl_add_u64 v[6:7], v[2:3], 0, v[176:177]
	s_mov_b32 s2, m0
	s_mov_b32 m0, s39
	s_nop 0
	global_load_lds_dwordx4 v[6:7], off
	s_mov_b32 m0, s2
	v_lshl_add_u64 v[6:7], v[4:5], 0, v[176:177]
	s_mov_b32 s2, m0
	s_mov_b32 m0, s40
	s_nop 0
	global_load_lds_dwordx4 v[6:7], off
	s_mov_b32 m0, s2
	v_lshl_add_u64 v[2:3], v[2:3], 0, v[178:179]
	s_mov_b32 s2, m0
	s_mov_b32 m0, s41
	s_nop 0
	global_load_lds_dwordx4 v[2:3], off
	s_mov_b32 m0, s2
	v_lshl_add_u64 v[2:3], v[4:5], 0, v[178:179]
	s_mov_b32 s2, m0
	s_mov_b32 m0, s42
	s_nop 0
	global_load_lds_dwordx4 v[2:3], off
	s_mov_b32 m0, s2
	s_or_b32 s2, s21, 0x100
	s_mul_hi_i32 s3, s2, 0x1400
	s_mulk_i32 s2, 0x1400
	s_add_u32 s2, s58, s2
	s_addc_u32 s3, s59, s3
	s_add_u32 s2, s2, s0
	s_addc_u32 s3, s3, s1
	v_lshl_add_u64 v[2:3], s[2:3], 0, v[168:169]
	v_lshl_add_u64 v[2:3], v[2:3], 0, s[14:15]
	v_lshl_add_u64 v[4:5], s[2:3], 0, v[170:171]
	v_lshl_add_u64 v[4:5], v[4:5], 0, s[16:17]
	v_lshl_add_u64 v[6:7], v[2:3], 0, v[172:173]
	s_mov_b32 s2, m0
	s_mov_b32 m0, s43
	s_nop 0
	global_load_lds_dwordx4 v[6:7], off
	s_mov_b32 m0, s2
	v_lshl_add_u64 v[6:7], v[4:5], 0, v[172:173]
	s_mov_b32 s2, m0
	s_mov_b32 m0, s44
	s_nop 0
	global_load_lds_dwordx4 v[6:7], off
	s_mov_b32 m0, s2
	v_lshl_add_u64 v[6:7], v[2:3], 0, v[174:175]
	s_mov_b32 s2, m0
	s_mov_b32 m0, s45
	s_nop 0
	global_load_lds_dwordx4 v[6:7], off
	s_mov_b32 m0, s2
	v_lshl_add_u64 v[6:7], v[4:5], 0, v[174:175]
	s_mov_b32 s2, m0
	s_mov_b32 m0, s46
	s_nop 0
	global_load_lds_dwordx4 v[6:7], off
	s_mov_b32 m0, s2
	v_lshl_add_u64 v[6:7], v[2:3], 0, v[176:177]
	s_mov_b32 s2, m0
	s_mov_b32 m0, s47
	s_nop 0
	global_load_lds_dwordx4 v[6:7], off
	s_mov_b32 m0, s2
	v_lshl_add_u64 v[6:7], v[4:5], 0, v[176:177]
	s_mov_b32 s2, m0
	s_mov_b32 m0, s48
	s_nop 0
	global_load_lds_dwordx4 v[6:7], off
	s_mov_b32 m0, s2
	v_lshl_add_u64 v[2:3], v[2:3], 0, v[178:179]
	s_mov_b32 s2, m0
	s_mov_b32 m0, s49
	s_nop 0
	global_load_lds_dwordx4 v[2:3], off
	s_mov_b32 m0, s2
	v_lshl_add_u64 v[2:3], v[4:5], 0, v[178:179]
	s_mov_b32 s2, m0
	s_mov_b32 m0, s50
	s_nop 0
	global_load_lds_dwordx4 v[2:3], off
	s_mov_b32 m0, s2
	s_add_u32 s2, s58, s0
	v_add_u32_e32 v186, s54, v198
	s_addc_u32 s3, s59, s1
	v_add_u32_e32 v188, s53, v186
	v_mov_b64_e32 v[10:11], s[2:3]
	v_mad_i64_i32 v[2:3], s[0:1], v188, s29, v[10:11]
	v_lshl_add_u64 v[6:7], v[2:3], 0, v[162:163]
	global_load_dwordx4 v[2:5], v[6:7], off
	s_nop 0
	global_load_dwordx4 v[6:9], v[6:7], off offset:64
	v_or_b32_e32 v192, 16, v186
	v_add_u32_e32 v190, s53, v192
	v_mad_i64_i32 v[10:11], s[0:1], v190, s29, v[10:11]
	v_lshl_add_u64 v[14:15], v[10:11], 0, v[162:163]
	global_load_dwordx4 v[10:13], v[14:15], off
	v_ashrrev_i32_e32 v189, 31, v188
	global_load_dwordx4 v[14:17], v[14:15], off offset:64
	v_add_u32_e32 v225, s54, v200
	v_or_b32_e32 v226, 16, v225
	v_add_u32_e32 v227, s53, v225
	v_add_u32_e32 v228, s53, v226
	v_mov_b64_e32 v[230:231], s[2:3]
	v_mad_i64_i32 v[232:233], s[0:1], v227, s29, v[230:231]
	v_lshl_add_u64 v[232:233], v[232:233], 0, v[162:163]
	global_load_dwordx4 v[240:243], v[232:233], off
	global_load_dwordx4 v[244:247], v[232:233], off offset:64
	v_mad_i64_i32 v[234:235], s[0:1], v228, s29, v[230:231]
	v_lshl_add_u64 v[234:235], v[234:235], 0, v[162:163]
	global_load_dwordx4 v[248:251], v[234:235], off
	global_load_dwordx4 v[252:255], v[234:235], off offset:64
	s_waitcnt vmcnt(0)
	s_barrier
; #define LAS __attribute__((address_space(3)))
; template <bool CAUSAL, bool SHARED> ...
;     ...
;     ka[0] = *(LAS const h16x8*)(Ka + kof0); ka[1] = *(LAS const h16x8*)(Ka + kof1); ka[2] = *(LAS const h16x8*)(Ka + 2048 + kof0); ka[3] = *(LAS const h16x8*)(Ka + 2048 + kof1);
; __device__ __forceinline__ void moba_load_q(const f16_t* qrow, int G, float maxgk, h16x8& q0, h16x8& q1, float& mb) {
;     const h16x8 r0v = *(const h16x8*)(qrow + 8 * G), r1v = *(const h16x8*)(qrow + 32 + 8 * G);
;     float q[16], n2 = 0.f;
; #pragma unroll
;     for (int j = 0; j < 8; ++j) { q[j] = (float)r0v[j]; q[8 + j] = (float)r1v[j]; n2 += q[j] * q[j] + q[8 + j] * q[8 + j]; }
;     n2 += __shfl_xor(n2, 16); n2 += __shfl_xor(n2, 32);
;     mb = (sqrtf(n2) * maxgk - BOUND_SHIFT) * LOG2E;
	ds_read_b128 v[118:121], v209 offset:2048
	ds_read_b128 v[122:125], v209
	ds_read_b128 v[126:129], v207 offset:2048
	ds_read_b128 v[114:117], v207
	v_ashrrev_i32_e32 v191, 31, v190
	s_mov_b32 s21, 0
	s_mov_b32 s24, 0
	s_mov_b32 s25, 0
	v_mov_b32_e32 v82, 0
	v_mov_b32_e32 v83, v163
	v_mov_b32_e32 v84, v163
	v_mov_b32_e32 v85, v163
	v_mov_b32_e32 v32, v163
	v_mov_b32_e32 v33, v163
	v_mov_b32_e32 v94, 0
	v_mov_b32_e32 v95, v163
	v_mov_b32_e32 v96, v163
	v_mov_b32_e32 v97, v163
	s_waitcnt vmcnt(3)
	v_cvt_f32_f16_e32 v18, v2
	v_cvt_f32_f16_sdwa v19, v2 dst_sel:DWORD dst_unused:UNUSED_PAD src0_sel:WORD_1
	s_waitcnt vmcnt(2)
	v_cvt_f32_f16_e32 v22, v6
	v_cvt_f32_f16_sdwa v23, v6 dst_sel:DWORD dst_unused:UNUSED_PAD src0_sel:WORD_1
	v_cvt_f32_f16_e32 v6, v7
	v_cvt_f32_f16_sdwa v7, v7 dst_sel:DWORD dst_unused:UNUSED_PAD src0_sel:WORD_1
	v_cvt_f32_f16_e32 v2, v3
	v_cvt_f32_f16_sdwa v3, v3 dst_sel:DWORD dst_unused:UNUSED_PAD src0_sel:WORD_1
	v_pk_mul_f32 v[24:25], v[18:19], s[18:19] op_sel_hi:[1,0]
	v_cvt_f32_f16_e32 v20, v4
	v_cvt_pk_f16_f32 v86, v24, v25
	v_cvt_f32_f16_e32 v24, v8
	v_cvt_f32_f16_sdwa v25, v8 dst_sel:DWORD dst_unused:UNUSED_PAD src0_sel:WORD_1
	v_cvt_f32_f16_sdwa v21, v4 dst_sel:DWORD dst_unused:UNUSED_PAD src0_sel:WORD_1
	v_pk_mul_f32 v[28:29], v[22:23], v[22:23]
	v_pk_mul_f32 v[30:31], v[6:7], v[6:7]
	v_pk_fma_f32 v[18:19], v[18:19], v[18:19], v[28:29]
	v_cvt_f32_f16_e32 v8, v9
	v_cvt_f32_f16_sdwa v9, v9 dst_sel:DWORD dst_unused:UNUSED_PAD src0_sel:WORD_1
	v_cvt_f32_f16_e32 v4, v5
	v_cvt_f32_f16_sdwa v5, v5 dst_sel:DWORD dst_unused:UNUSED_PAD src0_sel:WORD_1
	v_pk_mul_f32 v[26:27], v[2:3], s[18:19] op_sel_hi:[1,0]
	v_pk_fma_f32 v[2:3], v[2:3], v[2:3], v[30:31]
	v_add_f32_e32 v18, v18, v19
	v_pk_mul_f32 v[28:29], v[24:25], v[24:25]
	v_add_f32_e32 v2, v2, v18
	v_pk_fma_f32 v[28:29], v[20:21], v[20:21], v[28:29]
	v_add_f32_e32 v2, v3, v2
	v_pk_mul_f32 v[30:31], v[8:9], v[8:9]
	v_add_f32_e32 v2, v28, v2
	v_pk_fma_f32 v[30:31], v[4:5], v[4:5], v[30:31]
	v_add_f32_e32 v2, v29, v2
	v_add_f32_e32 v2, v30, v2
	v_add_f32_e32 v18, v31, v2
	ds_bpermute_b32 v19, v1, v18
	v_pk_mul_f32 v[2:3], v[20:21], s[18:19] op_sel_hi:[1,0]
	s_waitcnt vmcnt(0)
	v_cvt_f32_f16_e32 v20, v16
	v_cvt_pk_f16_f32 v88, v2, v3
	v_pk_mul_f32 v[2:3], v[4:5], s[18:19] op_sel_hi:[1,0]
	s_waitcnt lgkmcnt(0)
	v_add_f32_e32 v4, v18, v19
	ds_bpermute_b32 v5, v196, v4
	v_cvt_pk_f16_f32 v89, v2, v3
	v_pk_mul_f32 v[2:3], v[22:23], s[18:19] op_sel_hi:[1,0]
	v_cvt_f32_f16_e32 v18, v14
	v_cvt_pk_f16_f32 v90, v2, v3
	s_waitcnt lgkmcnt(0)
; __device__ __forceinline__ unsigned pkh(float lo, float hi) { f32x2 v = {lo, hi}; h16x2 h = __builtin_convertvector(v, h16x2); return __builtin_bit_cast(unsigned, h); }
; template <bool CAUSAL, bool SHARED> ...
;     ...
;     const f32x4 nma = {-mba, -mba, -mba, -mba}, nmb = {-mbb, -mbb, -mbb, -mbb};
; __device__ __forceinline__ void moba_load_q(const f16_t* qrow, int G, float maxgk, h16x8& q0, h16x8& q1, float& mb) {
;     ...
;     for (int j = 0; j < 8; ++j) { q[j] = (float)r0v[j]; q[8 + j] = (float)r1v[j]; n2 += q[j] * q[j] + q[8 + j] * q[8 + j]; }
;     n2 += __shfl_xor(n2, 16); n2 += __shfl_xor(n2, 32);
;     mb = (sqrtf(n2) * maxgk - BOUND_SHIFT) * LOG2E;
;     const float c = 0.125f * LOG2E;
;     u32x4 w0, w1;
;     w0.x = pkh(q[0] * c, q[1] * c); w0.y = pkh(q[2] * c, q[3] * c); w0.z = pkh(q[4] * c, q[5] * c); w0.w = pkh(q[6] * c, q[7] * c);
;     w1.x = pkh(q[8] * c, q[9] * c); w1.y = pkh(q[10] * c, q[11] * c); w1.z = pkh(q[12] * c, q[13] * c); w1.w = pkh(q[14] * c, q[15] * c);
;     q0 = __builtin_bit_cast(h16x8, w0); q1 = __builtin_bit_cast(h16x8, w1);
	v_add_f32_e32 v4, v4, v5
	v_mul_f32_e32 v5, 0x4f800000, v4
	v_cmp_gt_f32_e32 vcc, s31, v4
	v_pk_mul_f32 v[2:3], v[6:7], s[18:19] op_sel_hi:[1,0]
	v_cvt_f32_f16_sdwa v19, v14 dst_sel:DWORD dst_unused:UNUSED_PAD src0_sel:WORD_1
	v_cndmask_b32_e32 v4, v4, v5, vcc
	v_sqrt_f32_e32 v5, v4
	v_cvt_pk_f16_f32 v91, v2, v3
	v_pk_mul_f32 v[2:3], v[24:25], s[18:19] op_sel_hi:[1,0]
	v_cvt_f32_f16_e32 v14, v15
	v_cvt_pk_f16_f32 v92, v2, v3
	v_add_u32_e32 v2, -1, v5
	v_fma_f32 v3, -v2, v5, v4
	v_cmp_ge_f32_e64 s[0:1], 0, v3
	v_add_u32_e32 v3, 1, v5
	v_cvt_f32_f16_sdwa v15, v15 dst_sel:DWORD dst_unused:UNUSED_PAD src0_sel:WORD_1
	v_cndmask_b32_e64 v2, v5, v2, s[0:1]
	v_fma_f32 v5, -v3, v5, v4
	v_cmp_lt_f32_e64 s[0:1], 0, v5
	v_cvt_f32_f16_sdwa v5, v11 dst_sel:DWORD dst_unused:UNUSED_PAD src0_sel:WORD_1
	v_cvt_f32_f16_sdwa v21, v16 dst_sel:DWORD dst_unused:UNUSED_PAD src0_sel:WORD_1
	v_cndmask_b32_e64 v2, v2, v3, s[0:1]
	v_mul_f32_e32 v3, 0x37800000, v2
	v_cndmask_b32_e32 v2, v2, v3, vcc
	v_cmp_class_f32_e32 vcc, v4, v219
	v_cvt_f32_f16_e32 v16, v17
	v_cvt_f32_f16_sdwa v17, v17 dst_sel:DWORD dst_unused:UNUSED_PAD src0_sel:WORD_1
	v_cndmask_b32_e32 v2, v2, v4, vcc
	v_fma_f32 v24, v197, v2, -4.0
	v_pk_mul_f32 v[2:3], v[8:9], s[18:19] op_sel_hi:[1,0]
	v_cvt_f32_f16_e32 v4, v11
	v_cvt_pk_f16_f32 v93, v2, v3
	v_cvt_f32_f16_e32 v2, v10
	v_cvt_f32_f16_sdwa v3, v10 dst_sel:DWORD dst_unused:UNUSED_PAD src0_sel:WORD_1
	v_cvt_f32_f16_e32 v8, v12
	v_cvt_f32_f16_sdwa v9, v12 dst_sel:DWORD dst_unused:UNUSED_PAD src0_sel:WORD_1
	v_cvt_f32_f16_e32 v10, v13
	v_cvt_f32_f16_sdwa v11, v13 dst_sel:DWORD dst_unused:UNUSED_PAD src0_sel:WORD_1
	v_pk_mul_f32 v[12:13], v[18:19], v[18:19]
	v_pk_mul_f32 v[6:7], v[2:3], s[18:19] op_sel_hi:[1,0]
	v_pk_fma_f32 v[2:3], v[2:3], v[2:3], v[12:13]
	v_pk_mul_f32 v[12:13], v[14:15], v[14:15]
	v_cvt_pk_f16_f32 v98, v6, v7
	v_pk_mul_f32 v[6:7], v[4:5], s[18:19] op_sel_hi:[1,0]
	v_pk_fma_f32 v[4:5], v[4:5], v[4:5], v[12:13]
	v_add_f32_e32 v2, v2, v3
	v_pk_mul_f32 v[12:13], v[20:21], v[20:21]
	v_add_f32_e32 v2, v4, v2
	v_pk_fma_f32 v[12:13], v[8:9], v[8:9], v[12:13]
	v_add_f32_e32 v2, v5, v2
	v_pk_mul_f32 v[22:23], v[16:17], v[16:17]
	v_add_f32_e32 v2, v12, v2
	v_pk_fma_f32 v[22:23], v[10:11], v[10:11], v[22:23]
	v_add_f32_e32 v2, v13, v2
	v_add_f32_e32 v2, v22, v2
	v_add_f32_e32 v4, v23, v2
	ds_bpermute_b32 v5, v1, v4
	v_pk_mul_f32 v[2:3], v[8:9], s[18:19] op_sel_hi:[1,0]
	v_mul_f32_e32 v106, 0xbfb8aa3b, v24
	v_cvt_pk_f16_f32 v100, v2, v3
	v_pk_mul_f32 v[2:3], v[10:11], s[18:19] op_sel_hi:[1,0]
	s_waitcnt lgkmcnt(0)
	v_add_f32_e32 v4, v4, v5
	ds_bpermute_b32 v5, v196, v4
	v_cvt_pk_f16_f32 v101, v2, v3
	v_pk_mul_f32 v[2:3], v[18:19], s[18:19] op_sel_hi:[1,0]
	v_cvt_pk_f16_f32 v87, v26, v27
	v_cvt_pk_f16_f32 v102, v2, v3
	s_waitcnt lgkmcnt(0)
	v_add_f32_e32 v4, v4, v5
	v_mul_f32_e32 v5, 0x4f800000, v4
	v_cmp_gt_f32_e32 vcc, s31, v4
	v_pk_mul_f32 v[2:3], v[14:15], s[18:19] op_sel_hi:[1,0]
	v_cvt_pk_f16_f32 v99, v6, v7
	v_cndmask_b32_e32 v4, v4, v5, vcc
	v_sqrt_f32_e32 v5, v4
	v_cvt_pk_f16_f32 v103, v2, v3
	v_pk_mul_f32 v[2:3], v[20:21], s[18:19] op_sel_hi:[1,0]
	v_mov_b32_e32 v107, v106
	v_cvt_pk_f16_f32 v104, v2, v3
	v_add_u32_e32 v2, -1, v5
	v_fma_f32 v3, -v2, v5, v4
	v_cmp_ge_f32_e64 s[0:1], 0, v3
	v_add_u32_e32 v3, 1, v5
	v_mov_b32_e32 v108, v106
	v_cndmask_b32_e64 v2, v5, v2, s[0:1]
	v_fma_f32 v5, -v3, v5, v4
	v_cmp_lt_f32_e64 s[0:1], 0, v5
	v_mov_b32_e32 v109, v106
	v_mov_b32_e32 v5, v163
	v_cndmask_b32_e64 v2, v2, v3, s[0:1]
	v_mul_f32_e32 v3, 0x37800000, v2
	v_cndmask_b32_e32 v2, v2, v3, vcc
	v_cmp_class_f32_e32 vcc, v4, v219
	v_mov_b32_e32 v14, 0
	v_mov_b32_e32 v15, v163
	v_cndmask_b32_e32 v2, v2, v4, vcc
	v_fma_f32 v4, v197, v2, -4.0
	v_pk_mul_f32 v[2:3], v[16:17], s[18:19] op_sel_hi:[1,0]
	v_mul_f32_e32 v110, 0xbfb8aa3b, v4
	v_cvt_pk_f16_f32 v105, v2, v3
	v_mov_b32_e32 v111, v110
	v_mov_b32_e32 v112, v110
	v_mov_b32_e32 v113, v110
	v_mov_b32_e32 v2, 0
	v_mov_b32_e32 v3, v163
	v_mov_b32_e32 v4, v163
	v_mov_b32_e32 v16, v163
	v_mov_b32_e32 v17, v163
	v_mov_b32_e32 v10, 0
	v_mov_b32_e32 v11, v163
	v_mov_b32_e32 v12, v163
	v_mov_b32_e32 v13, v163
	v_mov_b32_e32 v6, 0
	v_mov_b32_e32 v7, v163
	v_mov_b32_e32 v8, v163
	v_mov_b32_e32 v9, v163
	v_mov_b32_e32 v18, 0
	v_mov_b32_e32 v19, v163
	v_mov_b32_e32 v20, v163
	v_mov_b32_e32 v21, v163
	v_mov_b32_e32 v26, 0
	v_mov_b32_e32 v27, v163
	v_mov_b32_e32 v28, v163
	v_mov_b32_e32 v29, v163
	v_mov_b32_e32 v22, 0
	v_mov_b32_e32 v23, v163
	v_mov_b32_e32 v24, v163
	v_mov_b32_e32 v25, v163
	v_mov_b32_e32 v30, 0
	v_mov_b32_e32 v31, v163
	s_branch .LBB0_1226

; __device__ __forceinline__ unsigned pk8(float a, float b, float c, float d) { int w = __builtin_amdgcn_cvt_pk_fp8_f32(a, b, 0, false); w = __builtin_amdgcn_cvt_pk_fp8_f32(c, d, w, true); return (unsigned)w; }
; __device__ __forceinline__ int pair16_dim(int G, int dt0) { return (G & 1) ? 16 * (dt0 + 1) + 4 * (G - 1) : 16 * dt0 + 4 * G; }
; __device__ __forceinline__ void store_o8(unsigned char* rowp, const f32x4 (&o)[4], float il, int G) {
;     const float c = il * F8_SY;
; #pragma unroll
;     for (int pr = 0; pr < 2; ++pr) { const int dt0 = 2 * pr;
;         const unsigned a = pk8(o[dt0][0] * c, o[dt0][1] * c, o[dt0][2] * c, o[dt0][3] * c), b = pk8(o[dt0 + 1][0] * c, o[dt0 + 1][1] * c, o[dt0 + 1][2] * c, o[dt0 + 1][3] * c);
;         const auto r = __builtin_amdgcn_permlane16_swap(a, b, false, false);
;         *(u32x2*)(rowp + pair16_dim(G, dt0)) = (u32x2){r[0], r[1]}; }
; __device__ __forceinline__ void moba_load_q(const f16_t* qrow, int G, float maxgk, h16x8& q0, h16x8& q1, float& mb) {
;     const h16x8 r0v = *(const h16x8*)(qrow + 8 * G), r1v = *(const h16x8*)(qrow + 32 + 8 * G);
;     float q[16], n2 = 0.f;
; #pragma unroll
;     for (int j = 0; j < 8; ++j) { q[j] = (float)r0v[j]; q[8 + j] = (float)r1v[j]; n2 += q[j] * q[j] + q[8 + j] * q[8 + j]; }
;     n2 += __shfl_xor(n2, 16); n2 += __shfl_xor(n2, 32);
.LBB0_1240:
	s_nop 0
	v_div_scale_f32 v32, s[24:25], v30, v30, 1.0
	v_rcp_f32_e32 v33, v32
	v_lshl_add_u64 v[186:187], v[164:165], 0, s[22:23]
	v_add_u32_e32 v192, s54, v200
	v_or_b32_e32 v194, 16, v192
	v_fma_f32 v86, -v32, v33, 1.0
	v_fmac_f32_e32 v33, v86, v33
	v_div_scale_f32 v86, vcc, 1.0, v30, 1.0
	v_mul_f32_e32 v87, v86, v33
	v_fma_f32 v88, -v32, v87, v86
	v_fmac_f32_e32 v87, v88, v33
	v_fma_f32 v32, -v32, v87, v86
	v_div_scale_f32 v86, s[22:23], v31, v31, 1.0
	v_rcp_f32_e32 v88, v86
	v_div_fmas_f32 v32, v32, v33, v87
	v_div_fixup_f32 v30, v32, v30, 1.0
	v_mul_f32_e32 v30, 0x42000000, v30
	v_fma_f32 v32, -v86, v88, 1.0
	v_fmac_f32_e32 v88, v32, v88
	v_div_scale_f32 v32, vcc, 1.0, v31, 1.0
	v_mul_f32_e32 v33, v32, v88
	v_fma_f32 v87, -v86, v33, v32
	v_fmac_f32_e32 v33, v87, v88
	v_fma_f32 v32, -v86, v33, v32
	v_div_fmas_f32 v86, v32, v88, v33
	v_mul_f32_e32 v33, v30, v82
	v_mul_f32_e32 v82, v30, v83
	v_mov_b32_e32 v32, 0
	v_cvt_pk_fp8_f32 v32, v33, v82
	v_mul_f32_e32 v26, v30, v26
	v_mul_f32_e32 v27, v30, v27
	v_mov_b32_e32 v33, 0
	v_cvt_pk_fp8_f32 v33, v26, v27
	v_mul_f32_e32 v27, v30, v29
	v_mul_f32_e32 v29, v30, v22
	v_mul_f32_e32 v23, v30, v23
	v_mov_b32_e32 v22, 0
	v_mul_f32_e32 v26, v30, v28
	v_div_fixup_f32 v28, v86, v31, 1.0
	v_cvt_pk_fp8_f32 v22, v29, v23
	v_mul_f32_e32 v18, v30, v18
	v_mul_f32_e32 v19, v30, v19
	v_mov_b32_e32 v23, 0
	v_cvt_pk_fp8_f32 v23, v18, v19
	v_mul_f32_e32 v18, v30, v20
	v_mul_f32_e32 v20, 0x42000000, v28
	v_mul_f32_e32 v19, v30, v21
	v_mul_f32_e32 v21, v20, v14
	v_mul_f32_e32 v15, v20, v15
	v_mov_b32_e32 v14, 0
	v_cvt_pk_fp8_f32 v14, v21, v15
	v_mul_f32_e32 v10, v20, v10
	v_mul_f32_e32 v11, v20, v11
	v_mov_b32_e32 v15, 0
	v_cvt_pk_fp8_f32 v15, v10, v11
	v_mul_f32_e32 v10, v20, v12
	v_mul_f32_e32 v12, v20, v6
	v_mul_f32_e32 v7, v20, v7
	v_mov_b32_e32 v6, 0
	v_cvt_pk_fp8_f32 v6, v12, v7
	v_mul_f32_e32 v2, v20, v2
	v_mul_f32_e32 v3, v20, v3
	v_mov_b32_e32 v7, 0
	v_cvt_pk_fp8_f32 v7, v2, v3
	v_mul_f32_e32 v16, v20, v16
	v_mul_f32_e32 v17, v20, v17
	v_mul_f32_e32 v11, v20, v13
	v_mul_f32_e32 v8, v20, v8
	v_mul_f32_e32 v9, v20, v9
	v_mul_f32_e32 v2, v20, v4
	v_mul_f32_e32 v3, v20, v5
	v_mul_f32_e32 v83, v30, v84
	v_mul_f32_e32 v84, v30, v85
	v_mul_f32_e32 v24, v30, v24
	v_mul_f32_e32 v25, v30, v25
	v_cvt_pk_fp8_f32 v14, v16, v17 op_sel:[0,0,1]
	v_cvt_pk_fp8_f32 v15, v10, v11 op_sel:[0,0,1]
	v_cvt_pk_fp8_f32 v6, v8, v9 op_sel:[0,0,1]
	v_cvt_pk_fp8_f32 v7, v2, v3 op_sel:[0,0,1]
	v_cvt_pk_fp8_f32 v32, v83, v84 op_sel:[0,0,1]
	v_cvt_pk_fp8_f32 v33, v26, v27 op_sel:[0,0,1]
	v_cvt_pk_fp8_f32 v22, v24, v25 op_sel:[0,0,1]
	v_cvt_pk_fp8_f32 v23, v18, v19 op_sel:[0,0,1]
	v_lshlrev_b64 v[10:11], 10, v[190:191]
	v_lshlrev_b64 v[26:27], 10, v[188:189]
	v_permlane16_swap_b32_e32 v14, v15
	v_lshl_add_u64 v[2:3], v[186:187], 0, v[10:11]
	v_permlane16_swap_b32_e32 v6, v7
	v_add_u32_e32 v188, s53, v192
	v_permlane16_swap_b32_e32 v32, v33
	v_lshl_add_u64 v[18:19], v[186:187], 0, v[26:27]
	v_permlane16_swap_b32_e32 v22, v23
	global_store_dwordx2 v[2:3], v[14:15], off
	global_store_dwordx2 v[2:3], v[6:7], off offset:32
	global_store_dwordx2 v[18:19], v[32:33], off
	global_store_dwordx2 v[18:19], v[22:23], off offset:32
	v_add_u32_e32 v190, s53, v194
	s_andn2_b64 vcc, exec, s[12:13]
	s_mov_b32 s22, 0
	v_cvt_f32_f16_e32 v32, v240
	v_cvt_f32_f16_e32 v24, v244
	v_cvt_f32_f16_sdwa v25, v244 dst_sel:DWORD dst_unused:UNUSED_PAD src0_sel:WORD_1
	v_cvt_f32_f16_sdwa v33, v240 dst_sel:DWORD dst_unused:UNUSED_PAD src0_sel:WORD_1
	v_cvt_f32_f16_e32 v22, v245
	v_cvt_f32_f16_sdwa v23, v245 dst_sel:DWORD dst_unused:UNUSED_PAD src0_sel:WORD_1
	v_cvt_f32_f16_e32 v30, v241
	v_cvt_f32_f16_sdwa v31, v241 dst_sel:DWORD dst_unused:UNUSED_PAD src0_sel:WORD_1
	v_cvt_f32_f16_e32 v14, v246
	v_cvt_f32_f16_sdwa v15, v246 dst_sel:DWORD dst_unused:UNUSED_PAD src0_sel:WORD_1
	v_cvt_f32_f16_e32 v28, v242
	v_cvt_f32_f16_sdwa v29, v242 dst_sel:DWORD dst_unused:UNUSED_PAD src0_sel:WORD_1
	v_pk_mul_f32 v[2:3], v[24:25], v[24:25]
	v_cvt_f32_f16_e32 v26, v243
	v_cvt_f32_f16_sdwa v27, v243 dst_sel:DWORD dst_unused:UNUSED_PAD src0_sel:WORD_1
	v_pk_fma_f32 v[4:5], v[32:33], v[32:33], v[2:3]
	v_pk_mul_f32 v[6:7], v[22:23], v[22:23]
	v_cvt_f32_f16_e32 v2, v247
	v_cvt_f32_f16_sdwa v3, v247 dst_sel:DWORD dst_unused:UNUSED_PAD src0_sel:WORD_1
	v_pk_fma_f32 v[6:7], v[30:31], v[30:31], v[6:7]
	v_add_f32_e32 v4, v4, v5
	v_pk_mul_f32 v[8:9], v[14:15], v[14:15]
	v_add_f32_e32 v4, v6, v4
	v_pk_fma_f32 v[8:9], v[28:29], v[28:29], v[8:9]
	v_add_f32_e32 v4, v7, v4
	v_pk_mul_f32 v[10:11], v[2:3], v[2:3]
	v_add_f32_e32 v4, v8, v4
	v_pk_fma_f32 v[10:11], v[26:27], v[26:27], v[10:11]
	v_add_f32_e32 v4, v9, v4
	v_add_f32_e32 v4, v10, v4
	v_add_f32_e32 v90, v11, v4
	v_cvt_f32_f16_e32 v10, v252
	v_cvt_f32_f16_sdwa v11, v252 dst_sel:DWORD dst_unused:UNUSED_PAD src0_sel:WORD_1
	v_cvt_f32_f16_e32 v6, v248
	v_cvt_f32_f16_sdwa v7, v248 dst_sel:DWORD dst_unused:UNUSED_PAD src0_sel:WORD_1
	v_cvt_f32_f16_e32 v20, v253
	v_cvt_f32_f16_sdwa v21, v253 dst_sel:DWORD dst_unused:UNUSED_PAD src0_sel:WORD_1
	v_cvt_f32_f16_e32 v8, v249
	v_cvt_f32_f16_sdwa v9, v249 dst_sel:DWORD dst_unused:UNUSED_PAD src0_sel:WORD_1
	v_cvt_f32_f16_e32 v16, v254
	v_cvt_f32_f16_sdwa v17, v254 dst_sel:DWORD dst_unused:UNUSED_PAD src0_sel:WORD_1
	v_cvt_f32_f16_e32 v12, v250
	v_cvt_f32_f16_sdwa v13, v250 dst_sel:DWORD dst_unused:UNUSED_PAD src0_sel:WORD_1
	v_pk_mul_f32 v[4:5], v[10:11], v[10:11]
	v_pk_mul_f32 v[86:87], v[20:21], v[20:21]
	v_pk_fma_f32 v[82:83], v[6:7], v[6:7], v[4:5]
	v_cvt_f32_f16_e32 v4, v255
	v_cvt_f32_f16_sdwa v5, v255 dst_sel:DWORD dst_unused:UNUSED_PAD src0_sel:WORD_1
	v_cvt_f32_f16_e32 v18, v251
	v_cvt_f32_f16_sdwa v19, v251 dst_sel:DWORD dst_unused:UNUSED_PAD src0_sel:WORD_1
	v_pk_fma_f32 v[84:85], v[8:9], v[8:9], v[86:87]
	v_add_f32_e32 v82, v82, v83
	v_pk_mul_f32 v[86:87], v[16:17], v[16:17]
	v_add_f32_e32 v82, v84, v82
	v_pk_fma_f32 v[86:87], v[12:13], v[12:13], v[86:87]
	v_add_f32_e32 v82, v85, v82
	v_pk_mul_f32 v[88:89], v[4:5], v[4:5]
	v_add_f32_e32 v82, v86, v82
	v_pk_fma_f32 v[88:89], v[18:19], v[18:19], v[88:89]
	v_add_f32_e32 v82, v87, v82
	v_add_f32_e32 v82, v88, v82
	v_add_f32_e32 v82, v89, v82
	ds_bpermute_b32 v91, v1, v90
	ds_bpermute_b32 v83, v1, v82
	s_waitcnt lgkmcnt(1)
	v_add_f32_e32 v84, v90, v91
	s_waitcnt lgkmcnt(0)
	v_add_f32_e32 v82, v82, v83
	ds_bpermute_b32 v85, v196, v84
	ds_bpermute_b32 v83, v196, v82
	s_cbranch_vccnz .LBB0_1245
; #define LAS __attribute__((address_space(3)))
; __device__ __forceinline__ unsigned pkh(float lo, float hi) { f32x2 v = {lo, hi}; h16x2 h = __builtin_convertvector(v, h16x2); return __builtin_bit_cast(unsigned, h); }
; template <bool CAUSAL, bool SHARED> ...
;     ...
;     ka[0] = *(LAS const h16x8*)(Ka + kof0); ka[1] = *(LAS const h16x8*)(Ka + kof1); ka[2] = *(LAS const h16x8*)(Ka + 2048 + kof0); ka[3] = *(LAS const h16x8*)(Ka + 2048 + kof1);
; __device__ __forceinline__ void moba_load_q(const f16_t* qrow, int G, float maxgk, h16x8& q0, h16x8& q1, float& mb) {
;     ...
;     for (int j = 0; j < 8; ++j) { q[j] = (float)r0v[j]; q[8 + j] = (float)r1v[j]; n2 += q[j] * q[j] + q[8 + j] * q[8 + j]; }
;     n2 += __shfl_xor(n2, 16); n2 += __shfl_xor(n2, 32);
;     mb = (sqrtf(n2) * maxgk - BOUND_SHIFT) * LOG2E;
;     const float c = 0.125f * LOG2E;
;     u32x4 w0, w1;
;     w0.x = pkh(q[0] * c, q[1] * c); w0.y = pkh(q[2] * c, q[3] * c); w0.z = pkh(q[4] * c, q[5] * c); w0.w = pkh(q[6] * c, q[7] * c);
;     w1.x = pkh(q[8] * c, q[9] * c); w1.y = pkh(q[10] * c, q[11] * c); w1.z = pkh(q[12] * c, q[13] * c); w1.w = pkh(q[14] * c, q[15] * c);
;     q0 = __builtin_bit_cast(h16x8, w0); q1 = __builtin_bit_cast(h16x8, w1);
	v_pk_mul_f32 v[24:25], v[24:25], s[18:19] op_sel_hi:[1,0]
	v_pk_mul_f32 v[14:15], v[14:15], s[18:19] op_sel_hi:[1,0]
	v_cvt_pk_f16_f32 v90, v24, v25
	s_waitcnt lgkmcnt(1)
	v_add_f32_e32 v24, v84, v85
	v_mul_f32_e32 v25, 0x4f800000, v24
	v_cmp_gt_f32_e32 vcc, s31, v24
	v_pk_mul_f32 v[22:23], v[22:23], s[18:19] op_sel_hi:[1,0]
	v_cvt_pk_f16_f32 v92, v14, v15
	v_cndmask_b32_e32 v24, v24, v25, vcc
	v_sqrt_f32_e32 v25, v24
	v_cvt_pk_f16_f32 v91, v22, v23
	v_pk_mul_f32 v[2:3], v[2:3], s[18:19] op_sel_hi:[1,0]
	v_pk_mul_f32 v[32:33], v[32:33], s[18:19] op_sel_hi:[1,0]
	v_add_u32_e32 v15, -1, v25
	v_fma_f32 v22, -v15, v25, v24
	v_cmp_ge_f32_e64 s[2:3], 0, v22
	v_add_u32_e32 v22, 1, v25
	v_fma_f32 v23, -v22, v25, v24
	v_cndmask_b32_e64 v15, v25, v15, s[2:3]
	v_cmp_lt_f32_e64 s[2:3], 0, v23
	v_cvt_pk_f16_f32 v93, v2, v3
	v_pk_mul_f32 v[2:3], v[6:7], s[18:19] op_sel_hi:[1,0]
	v_cndmask_b32_e64 v15, v15, v22, s[2:3]
	v_mul_f32_e32 v22, 0x37800000, v15
	v_cndmask_b32_e32 v15, v15, v22, vcc
	v_cmp_class_f32_e32 vcc, v24, v219
	s_waitcnt lgkmcnt(0)
	v_add_f32_e32 v6, v82, v83
	v_cvt_pk_f16_f32 v94, v2, v3
	v_cndmask_b32_e32 v15, v15, v24, vcc
	v_pk_mul_f32 v[2:3], v[8:9], s[18:19] op_sel_hi:[1,0]
	v_mul_f32_e32 v7, 0x4f800000, v6
	v_cmp_gt_f32_e32 vcc, s31, v6
	v_cvt_pk_f16_f32 v95, v2, v3
	v_pk_mul_f32 v[2:3], v[12:13], s[18:19] op_sel_hi:[1,0]
	v_cndmask_b32_e32 v6, v6, v7, vcc
	v_cvt_pk_f16_f32 v96, v2, v3
	v_pk_mul_f32 v[2:3], v[18:19], s[18:19] op_sel_hi:[1,0]
	v_sqrt_f32_e32 v7, v6
	v_cvt_pk_f16_f32 v97, v2, v3
	v_pk_mul_f32 v[2:3], v[10:11], s[18:19] op_sel_hi:[1,0]
	v_fma_f32 v15, v197, v15, -4.0
	v_cvt_pk_f16_f32 v98, v2, v3
	v_pk_mul_f32 v[2:3], v[20:21], s[18:19] op_sel_hi:[1,0]
	v_pk_mul_f32 v[30:31], v[30:31], s[18:19] op_sel_hi:[1,0]
	v_cvt_pk_f16_f32 v99, v2, v3
	v_pk_mul_f32 v[2:3], v[16:17], s[18:19] op_sel_hi:[1,0]
	v_pk_mul_f32 v[28:29], v[28:29], s[18:19] op_sel_hi:[1,0]
	v_cvt_pk_f16_f32 v100, v2, v3
	v_add_u32_e32 v2, -1, v7
	v_fma_f32 v3, -v2, v7, v6
	v_cmp_ge_f32_e64 s[2:3], 0, v3
	v_add_u32_e32 v3, 1, v7
	v_pk_mul_f32 v[26:27], v[26:27], s[18:19] op_sel_hi:[1,0]
	v_cndmask_b32_e64 v2, v7, v2, s[2:3]
	v_fma_f32 v7, -v3, v7, v6
	v_cmp_lt_f32_e64 s[2:3], 0, v7
	v_mov_b32_e32 v14, 0
	v_mul_f32_e32 v102, 0xbfb8aa3b, v15
	v_cndmask_b32_e64 v2, v2, v3, s[2:3]
	v_mul_f32_e32 v3, 0x37800000, v2
	v_cndmask_b32_e32 v2, v2, v3, vcc
	v_cmp_class_f32_e32 vcc, v6, v219
	v_cvt_pk_f16_f32 v86, v32, v33
	v_cvt_pk_f16_f32 v87, v30, v31
	v_cndmask_b32_e32 v2, v2, v6, vcc
	v_fma_f32 v6, v197, v2, -4.0
	v_pk_mul_f32 v[2:3], v[4:5], s[18:19] op_sel_hi:[1,0]
	v_mul_f32_e32 v106, 0xbfb8aa3b, v6
	v_cvt_pk_f16_f32 v101, v2, v3
	v_add_u32_e32 v2, s34, v202
	v_add_u32_e32 v3, s34, v201
	ds_read_b128 v[114:117], v2
	ds_read_b128 v[110:113], v3
	v_add_u32_e32 v2, s30, v202
	v_add_u32_e32 v3, s30, v201
	ds_read_b128 v[122:125], v2
	ds_read_b128 v[118:121], v3
	v_cvt_pk_f16_f32 v88, v28, v29
	v_cvt_pk_f16_f32 v89, v26, v27
	v_mov_b32_e32 v103, v102
	v_mov_b32_e32 v104, v102
	v_mov_b32_e32 v105, v102
	v_mov_b32_e32 v107, v106
	v_mov_b32_e32 v108, v106
	v_mov_b32_e32 v109, v106
	v_mov_b32_e32 v169, v217
	v_mov_b32_e32 v171, v215
	v_mov_b32_e32 v189, v213
	v_mov_b32_e32 v191, v211
	v_mov_b32_e32 v193, v202
	v_mov_b32_e32 v195, v201
	s_mov_b32 s23, 0
	v_mov_b32_e32 v15, v14
	v_mov_b32_e32 v16, v14
	v_mov_b32_e32 v17, v14
	v_mov_b32_e32 v2, v14
	v_mov_b32_e32 v3, v14
	v_mov_b32_e32 v4, v14
	v_mov_b32_e32 v5, v14
	v_mov_b32_e32 v6, v14
	v_mov_b32_e32 v7, v14
	v_mov_b32_e32 v8, v14
	v_mov_b32_e32 v9, v14
	v_mov_b32_e32 v10, v14
	v_mov_b32_e32 v11, v14
	v_mov_b32_e32 v12, v14
	v_mov_b32_e32 v13, v14
	v_mov_b32_e32 v30, v14
	v_mov_b32_e32 v31, v14
	v_mov_b32_e32 v32, v14
	v_mov_b32_e32 v33, v14
	v_mov_b32_e32 v18, v14
	v_mov_b32_e32 v19, v14
	v_mov_b32_e32 v20, v14
	v_mov_b32_e32 v21, v14
	v_mov_b32_e32 v22, v14
	v_mov_b32_e32 v23, v14
	v_mov_b32_e32 v24, v14
	v_mov_b32_e32 v25, v14
	v_mov_b32_e32 v26, v14
	v_mov_b32_e32 v27, v14
	v_mov_b32_e32 v28, v14
	v_mov_b32_e32 v29, v14
	v_mov_b32_e32 v82, v14
	v_mov_b32_e32 v83, v14
	v_mov_b32_e32 v84, v14
	v_mov_b32_e32 v85, v14
	v_mov_b32_e32 v126, v14
	v_mov_b32_e32 v127, v14
	v_mov_b32_e32 v128, v14
	v_mov_b32_e32 v129, v14
	s_branch .LBB0_1243

; __global__ void __launch_bounds__(NWAVES * 64, 2) fwd_kernel(Args args) {
;     extern __shared__ __attribute__((aligned(16))) unsigned char lds_raw[];
	.amdhsa_kernel _Z10fwd_kernel4Args
		.amdhsa_group_segment_fixed_size 0
		.amdhsa_private_segment_fixed_size 0
		.amdhsa_kernarg_size 448
		.amdhsa_user_sgpr_count 2
		.amdhsa_user_sgpr_dispatch_ptr 0
		.amdhsa_user_sgpr_queue_ptr 0
		.amdhsa_user_sgpr_kernarg_segment_ptr 1
		.amdhsa_user_sgpr_dispatch_id 0
		.amdhsa_user_sgpr_kernarg_preload_length 0
		.amdhsa_user_sgpr_kernarg_preload_offset 0
		.amdhsa_user_sgpr_private_segment_size 0
		.amdhsa_uses_dynamic_stack 0
		.amdhsa_enable_private_segment 0
		.amdhsa_system_sgpr_workgroup_id_x 1
		.amdhsa_system_sgpr_workgroup_id_y 0
		.amdhsa_system_sgpr_workgroup_id_z 0
		.amdhsa_system_sgpr_workgroup_info 0
		.amdhsa_system_vgpr_workitem_id 0
		.amdhsa_next_free_vgpr 256
		.amdhsa_next_free_sgpr 98
		.amdhsa_accum_offset 256
		.amdhsa_reserve_vcc 1
		.amdhsa_float_round_mode_32 0
		.amdhsa_float_round_mode_16_64 0
		.amdhsa_float_denorm_mode_32 3
		.amdhsa_float_denorm_mode_16_64 3
		.amdhsa_dx10_clamp 1
		.amdhsa_ieee_mode 1
		.amdhsa_fp16_overflow 0
		.amdhsa_tg_split 0
		.amdhsa_exception_fp_ieee_invalid_op 0
		.amdhsa_exception_fp_denorm_src 0
		.amdhsa_exception_fp_ieee_div_zero 0
		.amdhsa_exception_fp_ieee_overflow 0
		.amdhsa_exception_fp_ieee_underflow 0
		.amdhsa_exception_fp_ieee_inexact 0
		.amdhsa_exception_int_div_zero 0
	.end_amdhsa_kernel

; __global__ void __launch_bounds__(NWAVES * 64, 2) fwd_kernel(Args args) {
;     extern __shared__ __attribute__((aligned(16))) unsigned char lds_raw[];
amdhsa.kernels:
  - .agpr_count:     0
    .args:
      - .offset:         0
        .size:           192
        .value_kind:     by_value
      - .offset:         192
        .size:           4
        .value_kind:     hidden_block_count_x
      - .offset:         196
        .size:           4
        .value_kind:     hidden_block_count_y
      - .offset:         200
        .size:           4
        .value_kind:     hidden_block_count_z
      - .offset:         204
        .size:           2
        .value_kind:     hidden_group_size_x
      - .offset:         206
        .size:           2
        .value_kind:     hidden_group_size_y
      - .offset:         208
        .size:           2
        .value_kind:     hidden_group_size_z
      - .offset:         210
        .size:           2
        .value_kind:     hidden_remainder_x
      - .offset:         212
        .size:           2
        .value_kind:     hidden_remainder_y
      - .offset:         214
        .size:           2
        .value_kind:     hidden_remainder_z
      - .offset:         232
        .size:           8
        .value_kind:     hidden_global_offset_x
      - .offset:         240
        .size:           8
        .value_kind:     hidden_global_offset_y
      - .offset:         248
        .size:           8
        .value_kind:     hidden_global_offset_z
      - .offset:         256
        .size:           2
        .value_kind:     hidden_grid_dims
      - .offset:         312
        .size:           4
        .value_kind:     hidden_dynamic_lds_size
    .group_segment_fixed_size: 0
    .kernarg_segment_align: 8
    .kernarg_segment_size: 448
    .language:       OpenCL C
    .language_version:
      - 2
      - 0
    .max_flat_workgroup_size: 512
    .name:           _Z10fwd_kernel4Args
    .private_segment_fixed_size: 0
    .sgpr_count:     104
    .sgpr_spill_count: 152
    .symbol:         _Z10fwd_kernel4Args.kd
    .uniform_work_group_size: 1
    .uses_dynamic_stack: false
    .vgpr_count:     256
    .vgpr_spill_count: 0
    .wavefront_size: 64
